# baseline (speedup 1.0000x reference)
;     __device__ __forceinline__ void a_ready(const Unit& u, int ui) const {
;         int t = threadIdx.x; asm volatile("" : "+v"(t));
;         if (t < 256) { const int r = u.pm * BM + t; const float qa = rsa[r] * (1.0f / 1024.0f) + RMS_EPS, qb = rsb[r] * (1.0f / 1024.0f) + RMS_EPS;
;             sc[(ui & 1) * 512 + t] = __builtin_amdgcn_rsqf(qb) * __builtin_amdgcn_sqrtf(qa); sc[(ui & 1) * 512 + 256 + t] = __builtin_amdgcn_rsqf(qa); }
; template <class Epi, class Sched, bool ALIGN_EPI = false, bool SP2 = false>
; __device__ __forceinline__ void gemm_phase(PG8_LAS unsigned char* lds, const Gemm g, const Sched& S, const Epi& E) {
;     ...
;             if (last && has_next) S.a_ready(nxt, ui + 1);
.LBB0_389:
	s_cmp_eq_u32 s64, 0xf780000
	s_cselect_b64 s[44:45], -1, 0
	s_branch .LBB0_386
.LBB0_392:
	s_andn2_b64 vcc, exec, s[6:7]
	s_cbranch_vccnz .Lar_noissue
	v_cmp_gt_i32_e32 vcc, s33, v168
	s_and_saveexec_b64 s[66:67], vcc
	s_cbranch_execz .Lar_issued
	v_add_u32_e32 v2, s81, v168
	v_ashrrev_i32_e32 v3, 31, v2
	v_lshlrev_b64 v[2:3], 2, v[2:3]
	v_lshl_add_u64 v[150:151], s[10:11], 0, v[2:3]
	v_lshl_add_u64 v[2:3], s[8:9], 0, v[2:3]
	global_load_dword v166, v[150:151], off
	global_load_dword v167, v[2:3], off
.Lar_issued:
	s_or_b64 exec, exec, s[66:67]
.Lar_noissue:
	s_and_b64 vcc, exec, s[20:21]
	s_cbranch_vccz .LBB0_394
	s_barrier

;     __device__ __forceinline__ void a_ready(const Unit& u, int ui) const {
;         int t = threadIdx.x; asm volatile("" : "+v"(t));
;         if (t < 256) { const int r = u.pm * BM + t; const float qa = rsa[r] * (1.0f / 1024.0f) + RMS_EPS, qb = rsb[r] * (1.0f / 1024.0f) + RMS_EPS;
;             sc[(ui & 1) * 512 + t] = __builtin_amdgcn_rsqf(qb) * __builtin_amdgcn_sqrtf(qa); sc[(ui & 1) * 512 + 256 + t] = __builtin_amdgcn_rsqf(qa); }
; template <class Epi, class Sched, bool ALIGN_EPI = false, bool SP2 = false>
; __device__ __forceinline__ void gemm_phase(PG8_LAS unsigned char* lds, const Gemm g, const Sched& S, const Epi& E) {
;     ...
;         if constexpr (!Epi::AFTER_DRAIN) { E(acc, cur, wr, wc, fr, fq, ui); S.done(cur); }
.LBB0_410:
	s_or_b64 exec, exec, s[42:43]
	s_andn2_b64 vcc, exec, s[6:7]
	s_cbranch_vccnz .Lar_nocons
	v_cmp_gt_i32_e32 vcc, s33, v168
	s_and_saveexec_b64 s[66:67], vcc
	s_cbranch_execz .Lar_consd
	v_fmamk_f32 v166, v166, 0x3a800000, v169
	v_sqrt_f32_e32 v3, v166
	v_fmamk_f32 v2, v167, 0x3a800000, v169
	v_rsq_f32_e32 v2, v2
	v_lshl_add_u32 v0, v168, 2, s82
	s_nop 0
	v_mul_f32_e32 v2, v3, v2
	v_rsq_f32_e32 v3, v166
	s_nop 1
	ds_write2st64_b32 v0, v2, v3 offset1:4

; #define PG8_BAR __builtin_amdgcn_s_barrier()
; template <class Epi, class Sched, bool ALIGN_EPI = false, bool SP2 = false>
; __device__ __forceinline__ void gemm_phase(PG8_LAS unsigned char* lds, const Gemm g, const Sched& S, const Epi& E) {
;     ...
;         if (!has_next) break;
; #pragma unroll
;         for (int a = 0; a < 2; ++a)
; #pragma unroll
;             for (int b = 0; b < 2; ++b)
; #pragma unroll
;                 for (int m = 0; m < 4; ++m)
; #pragma unroll
;                     for (int n = 0; n < 2; ++n) acc[a][b][m][n] = (f32x4){0.f, 0.f, 0.f, 0.f};
;         cur = nxt; cA = nA; cB = nB; ++ui;
;         if constexpr (ALIGN_EPI) { if (wr == 1) PG8_BAR; }
.Lar_nocons:
	s_andn2_b64 vcc, exec, s[6:7]
	s_mov_b64 s[6:7], -1
	s_cbranch_vccnz .LBB0_377
	s_andn2_b64 vcc, exec, s[12:13]
	s_cbranch_vccnz .LBB0_376
	s_barrier
	s_branch .LBB0_376
